# XCD-hierarchical grid barrier; released blocks skip the second redundant buffer_inv
# speedup vs baseline: 1.0186x; 1.0011x over previous
; __global__ void __launch_bounds__(512, 2) mega(Params p_, int ph_lo, int ph_hi, int coop) {
;     ...
;   for (int ph = ph_lo; ph < ph_hi; ph++) {
;     run_phase(p, ph, smem, 0);
;     if (coop && ph + 1 < ph_hi) cg::this_grid().sync();
.LBB0_1072:
	s_waitcnt vmcnt(0) lgkmcnt(0)
	s_barrier
	s_mov_b64 s[6:7], exec
	v_readlane_b32 s8, v226, 25
	v_readlane_b32 s9, v226, 26
	s_and_b64 s[8:9], s[6:7], s[8:9]
	s_mov_b64 exec, s[8:9]
	s_cbranch_execnz .LBB0_1073
.Lgb_to3:
	s_getpc_b64 s[98:99]
